# speedup vs baseline: 1.0094x; 1.0072x over previous
; #define EPI_FENCE(j) do { if ((j) == 0) asm volatile("" ::: "memory"); } while (0)
; __device__ __forceinline__ void phase_gemm1(const Params& p, int wid_s, char* shm) {
;     ...
;     if (pn < 12) {
;       const int hq = pn * 2 + (wc >> 1);
;       const bool isq = hq < 12;
;       u16* dst = isq ? Qb : Kb;
;       const int hh = isq ? hq : hq - 12;
;       const float scl = isq ? QSCALE : 1.f;
;       const int d = (wc & 1) * 32 + 2 * fr;
; #pragma unroll
;       for (int ai = 0; ai < 2; ++ai)
; #pragma unroll
;         for (int m = 0; m < 4; ++m)
; #pragma unroll
;           for (int j = 0; j < 4; ++j) { EPI_FENCE(j);
;             int tok = tokbase + ai * 128 + m * 16 + j;
;             int t = tok < 8192 ? (tok & 2047) : (tok & 4095);
;             u16* drow = dst + (size_t)tok * 1536 + hh * 128 + d;
;             float4 cs = *(const float4*)(rope + (t * 64 + d) * 2);
;             float a0 = acc[ai][0][m][0][j], a1 = acc[ai][0][m][1][j], b0 = acc[ai][1][m][0][j], b1 = acc[ai][1][m][1][j];
;             *(unsigned*)(drow) = pack2((a0 * cs.x - b0 * cs.y) * scl, (a1 * cs.z - b1 * cs.w) * scl);
;             *(unsigned*)(drow + 64) = pack2((b0 * cs.x + a0 * cs.y) * scl, (b1 * cs.z + a1 * cs.w) * scl);
.LBB0_194:
	s_andn2_b64 vcc, exec, s[66:67]
	s_cbranch_vccnz .LBB0_169
	s_lshl_b32 s2, s11, 1
	s_or_b32 s2, s2, s59
	s_cmp_lt_i32 s2, 12
	s_cselect_b64 vcc, -1, 0
	s_and_b64 s[64:65], vcc, exec
	s_mov_b32 s64, 0x12e00000
	s_cselect_b32 s64, s64, 0x1a600000
	s_add_u32 s66, s30, s64
	s_addc_u32 s67, s31, 0
	s_lshl_b32 s2, s2, 7
	s_add_i32 s68, s2, 0xfffffa00
	s_and_b64 s[64:65], vcc, exec
	s_cselect_b32 s64, s2, s68
	s_ashr_i32 s65, s64, 31
	s_lshl_b64 s[64:65], s[64:65], 1
	v_mov_b32_e32 v128, 0x3e0293ee
	v_lshl_or_b32 v131, v136, 1, s60
	s_add_u32 s64, s66, s64
	v_cndmask_b32_e32 v132, 1.0, v128, vcc
	s_addc_u32 s65, s67, s65
	v_lshlrev_b32_e32 v128, 1, v131
	v_cmp_gt_i32_e32 vcc, s61, v130
	v_lshl_add_u64 v[134:135], s[64:65], 0, v[128:129]
	v_mov_b32_e32 v150, v124
	v_cndmask_b32_e32 v128, v139, v140, vcc
	v_and_b32_e32 v133, v128, v130
	v_lshlrev_b32_e32 v128, 3, v131
	v_lshl_or_b32 v131, v133, 9, v128
	v_cmp_gt_i32_e64 s[98:99], s61, v130
	s_nop 1
	v_cndmask_b32_e64 v246, v139, v140, s[98:99]
	v_add_u32_e32 v242, 0x0, v130
	v_and_b32_e32 v242, v246, v242
	v_lshl_or_b32 v242, v242, 9, v128
	global_load_dwordx4 v[178:181], v242, s[4:5]
	v_add_u32_e32 v242, 0x1, v130
	v_and_b32_e32 v242, v246, v242
	v_lshl_or_b32 v242, v242, 9, v128
	global_load_dwordx4 v[182:185], v242, s[4:5]
	v_add_u32_e32 v242, 0x2, v130
	v_and_b32_e32 v242, v246, v242
	v_lshl_or_b32 v242, v242, 9, v128
	global_load_dwordx4 v[186:189], v242, s[4:5]
	v_add_u32_e32 v242, 0x3, v130
	v_and_b32_e32 v242, v246, v242
	v_lshl_or_b32 v242, v242, 9, v128
	global_load_dwordx4 v[190:193], v242, s[4:5]
	v_add_u32_e32 v242, 0x10, v130
	v_and_b32_e32 v242, v246, v242
	v_lshl_or_b32 v242, v242, 9, v128
	global_load_dwordx4 v[194:197], v242, s[4:5]
	v_add_u32_e32 v242, 0x11, v130
	v_and_b32_e32 v242, v246, v242
	v_lshl_or_b32 v242, v242, 9, v128
	global_load_dwordx4 v[198:201], v242, s[4:5]
	v_add_u32_e32 v242, 0x12, v130
	v_and_b32_e32 v242, v246, v242
	v_lshl_or_b32 v242, v242, 9, v128
	global_load_dwordx4 v[202:205], v242, s[4:5]
	v_add_u32_e32 v242, 0x13, v130
	v_and_b32_e32 v242, v246, v242
	v_lshl_or_b32 v242, v242, 9, v128
	global_load_dwordx4 v[206:209], v242, s[4:5]
	v_add_u32_e32 v242, 0x20, v130
	v_and_b32_e32 v242, v246, v242
	v_lshl_or_b32 v242, v242, 9, v128
	global_load_dwordx4 v[210:213], v242, s[4:5]
	v_add_u32_e32 v242, 0x21, v130
	v_and_b32_e32 v242, v246, v242
	v_lshl_or_b32 v242, v242, 9, v128
	global_load_dwordx4 v[214:217], v242, s[4:5]
	v_add_u32_e32 v242, 0x22, v130
	v_and_b32_e32 v242, v246, v242
	v_lshl_or_b32 v242, v242, 9, v128
	global_load_dwordx4 v[218:221], v242, s[4:5]
	v_add_u32_e32 v242, 0x23, v130
	v_and_b32_e32 v242, v246, v242
	v_lshl_or_b32 v242, v242, 9, v128
	global_load_dwordx4 v[222:225], v242, s[4:5]
	v_add_u32_e32 v242, 0x30, v130
	v_and_b32_e32 v242, v246, v242
	v_lshl_or_b32 v242, v242, 9, v128
	global_load_dwordx4 v[226:229], v242, s[4:5]
	v_add_u32_e32 v242, 0x31, v130
	v_and_b32_e32 v242, v246, v242
	v_lshl_or_b32 v242, v242, 9, v128
	global_load_dwordx4 v[230:233], v242, s[4:5]
	v_add_u32_e32 v242, 0x32, v130
	v_and_b32_e32 v242, v246, v242
	v_lshl_or_b32 v242, v242, 9, v128
	global_load_dwordx4 v[234:237], v242, s[4:5]
	v_add_u32_e32 v242, 0x33, v130
	v_and_b32_e32 v242, v246, v242
	v_lshl_or_b32 v242, v242, 9, v128
	global_load_dwordx4 v[238:241], v242, s[4:5]
	s_waitcnt vmcnt(15)
	v_mov_b32_e32 v142, v178
	v_mov_b32_e32 v143, v179
	v_mov_b32_e32 v144, v180
	v_mov_b32_e32 v145, v181
	v_mov_b32_e32 v151, v120
	v_mov_b32_e32 v146, v116
	v_mov_b32_e32 v147, v112
	s_movk_i32 s2, 0x1fff
	v_mad_i64_i32 v[136:137], s[64:65], v130, s9, v[134:135]
	v_cmp_gt_i32_e32 vcc, s2, v130
	s_movk_i32 s2, 0x1ffe
	v_mov_b32_e32 v152, v143
	v_mov_b32_e32 v153, v145
	v_mov_b32_e32 v148, v142
	v_mov_b32_e32 v149, v144
	v_pk_mul_f32 v[150:151], v[150:151], v[152:153]
	s_nop 0
	v_pk_fma_f32 v[146:147], v[146:147], v[148:149], v[150:151] neg_lo:[0,0,1] neg_hi:[0,0,1]
	v_mov_b32_e32 v148, v143
	v_pk_mul_f32 v[146:147], v[132:133], v[146:147] op_sel_hi:[0,1]
	v_mov_b32_e32 v150, v124
	v_mov_b32_e32 v151, v112
	v_mov_b32_e32 v143, v145
	v_cvt_pk_bf16_f32 v131, v146, v147
	v_mov_b32_e32 v146, v116
	v_mov_b32_e32 v147, v120
	v_pk_mul_f32 v[142:143], v[150:151], v[142:143]
	v_cndmask_b32_e32 v116, v139, v140, vcc
	v_pk_fma_f32 v[142:143], v[146:147], v[148:149], v[142:143]
	global_store_dword v[136:137], v131, off
	v_pk_mul_f32 v[142:143], v[132:133], v[142:143] op_sel_hi:[0,1]
	v_cvt_pk_bf16_f32 v112, v142, v143
	global_store_dword v[136:137], v112, off offset:128
	v_add_u32_e32 v112, 1, v130
	v_and_b32_e32 v116, v116, v112
	v_mad_i64_i32 v[136:137], s[64:65], v112, s9, v[134:135]
	v_lshl_or_b32 v112, v116, 9, v128
	s_waitcnt vmcnt(16)
	v_mov_b32_e32 v142, v182
	v_mov_b32_e32 v143, v183
	v_mov_b32_e32 v144, v184
	v_mov_b32_e32 v145, v185
	v_mov_b32_e32 v120, v125
	v_mov_b32_e32 v112, v117
	v_cmp_gt_i32_e32 vcc, s2, v130
	v_mov_b32_e32 v124, v126
	s_movk_i32 s2, 0x1ffd
	v_mov_b32_e32 v148, v143
	v_mov_b32_e32 v149, v145
	v_mov_b32_e32 v146, v142
	v_mov_b32_e32 v147, v144
	v_pk_mul_f32 v[148:149], v[120:121], v[148:149]
	v_mov_b32_e32 v116, v143
	v_pk_fma_f32 v[146:147], v[112:113], v[146:147], v[148:149] neg_lo:[0,0,1] neg_hi:[0,0,1]
	v_mov_b32_e32 v143, v145
	v_pk_mul_f32 v[146:147], v[132:133], v[146:147] op_sel_hi:[0,1]
	v_cvt_pk_bf16_f32 v112, v146, v147
	global_store_dword v[136:137], v112, off
	v_mov_b32_e32 v112, v125
	v_mov_b32_e32 v120, v117
	v_mov_b32_e32 v117, v144
	v_pk_mul_f32 v[112:113], v[112:113], v[142:143]
	v_mov_b32_e32 v125, v122
	v_pk_fma_f32 v[112:113], v[120:121], v[116:117], v[112:113]
	v_mov_b32_e32 v117, v114
	v_pk_mul_f32 v[112:113], v[132:133], v[112:113] op_sel_hi:[0,1]
	v_cvt_pk_bf16_f32 v112, v112, v113
	global_store_dword v[136:137], v112, off offset:128
	v_add_u32_e32 v112, 2, v130
	v_cndmask_b32_e32 v113, v139, v140, vcc
	v_and_b32_e32 v116, v113, v112
	v_lshl_or_b32 v116, v116, 9, v128
	s_waitcnt vmcnt(17)
; #define EPI_FENCE(j) do { if ((j) == 0) asm volatile("" ::: "memory"); } while (0)
; __device__ __forceinline__ void phase_gemm1(const Params& p, int wid_s, char* shm) {
;     ...
;       for (int ai = 0; ai < 2; ++ai)
; #pragma unroll
;         for (int m = 0; m < 4; ++m)
; #pragma unroll
;           for (int j = 0; j < 4; ++j) { EPI_FENCE(j);
;             int tok = tokbase + ai * 128 + m * 16 + j;
;             int t = tok < 8192 ? (tok & 2047) : (tok & 4095);
;             u16* drow = dst + (size_t)tok * 1536 + hh * 128 + d;
;             float4 cs = *(const float4*)(rope + (t * 64 + d) * 2);
;             float a0 = acc[ai][0][m][0][j], a1 = acc[ai][0][m][1][j], b0 = acc[ai][1][m][0][j], b1 = acc[ai][1][m][1][j];
;             *(unsigned*)(drow) = pack2((a0 * cs.x - b0 * cs.y) * scl, (a1 * cs.z - b1 * cs.w) * scl);
;             *(unsigned*)(drow + 64) = pack2((b0 * cs.x + a0 * cs.y) * scl, (b1 * cs.z + a1 * cs.w) * scl);
	v_mov_b32_e32 v142, v186
	v_mov_b32_e32 v143, v187
	v_mov_b32_e32 v144, v188
	v_mov_b32_e32 v145, v189
	v_mov_b32_e32 v116, v118
	v_mad_i64_i32 v[112:113], s[64:65], v112, s9, v[134:135]
	v_cmp_gt_i32_e32 vcc, s2, v130
	s_movk_i32 s2, 0x1ff0
	v_mov_b32_e32 v136, v143
	v_mov_b32_e32 v137, v145
	v_mov_b32_e32 v120, v142
	v_mov_b32_e32 v121, v144
	v_pk_mul_f32 v[124:125], v[124:125], v[136:137]
	s_nop 0
	v_pk_fma_f32 v[116:117], v[116:117], v[120:121], v[124:125] neg_lo:[0,0,1] neg_hi:[0,0,1]
	v_mov_b32_e32 v120, v143
	v_pk_mul_f32 v[116:117], v[132:133], v[116:117] op_sel_hi:[0,1]
	v_cvt_pk_bf16_f32 v116, v116, v117
	v_mov_b32_e32 v124, v126
	v_mov_b32_e32 v125, v114
	v_mov_b32_e32 v143, v145
	global_store_dword v[112:113], v116, off
	v_mov_b32_e32 v116, v118
	v_mov_b32_e32 v117, v122
	v_pk_mul_f32 v[124:125], v[124:125], v[142:143]
	v_mov_b32_e32 v122, v127
	v_pk_fma_f32 v[116:117], v[116:117], v[120:121], v[124:125]
	v_mov_b32_e32 v118, v100
	v_pk_mul_f32 v[116:117], v[132:133], v[116:117] op_sel_hi:[0,1]
	v_cvt_pk_bf16_f32 v114, v116, v117
	global_store_dword v[112:113], v114, off offset:128
	v_add_u32_e32 v112, 3, v130
	v_cndmask_b32_e32 v113, v139, v140, vcc
	v_and_b32_e32 v114, v113, v112
	v_lshl_or_b32 v114, v114, 9, v128
	s_waitcnt vmcnt(18)
	v_mov_b32_e32 v142, v190
	v_mov_b32_e32 v143, v191
	v_mov_b32_e32 v144, v192
	v_mov_b32_e32 v145, v193
	v_mov_b32_e32 v114, v119
	v_mad_i64_i32 v[112:113], s[64:65], v112, s9, v[134:135]
	v_cmp_gt_i32_e32 vcc, s2, v130
	s_movk_i32 s2, 0x1fef
	v_mov_b32_e32 v120, v143
	v_mov_b32_e32 v121, v145
	v_mov_b32_e32 v116, v142
	v_mov_b32_e32 v117, v144
	v_pk_mul_f32 v[120:121], v[122:123], v[120:121]
	v_mov_b32_e32 v122, v119
	v_pk_fma_f32 v[116:117], v[114:115], v[116:117], v[120:121] neg_lo:[0,0,1] neg_hi:[0,0,1]
	v_mov_b32_e32 v119, v96
	v_pk_mul_f32 v[116:117], v[132:133], v[116:117] op_sel_hi:[0,1]
	v_cvt_pk_bf16_f32 v114, v116, v117
	global_store_dword v[112:113], v114, off
	v_mov_b32_e32 v116, v143
	v_mov_b32_e32 v114, v127
	v_mov_b32_e32 v143, v145
	v_mov_b32_e32 v117, v144
	v_pk_mul_f32 v[114:115], v[114:115], v[142:143]
	s_nop 0
	v_pk_fma_f32 v[114:115], v[122:123], v[116:117], v[114:115]
	v_mov_b32_e32 v122, v108
	v_pk_mul_f32 v[114:115], v[132:133], v[114:115] op_sel_hi:[0,1]
	v_cvt_pk_bf16_f32 v114, v114, v115
	global_store_dword v[112:113], v114, off offset:128
	v_add_u32_e32 v112, 16, v130
	v_cndmask_b32_e32 v113, v139, v140, vcc
	v_and_b32_e32 v113, v113, v112
	v_mad_i64_i32 v[116:117], s[64:65], v112, s9, v[134:135]
	v_lshl_or_b32 v112, v113, 9, v128
	s_waitcnt vmcnt(19)
	v_mov_b32_e32 v112, v194
	v_mov_b32_e32 v113, v195
	v_mov_b32_e32 v114, v196
	v_mov_b32_e32 v115, v197
	v_mov_b32_e32 v123, v104
	v_cmp_gt_i32_e32 vcc, s2, v130
	s_movk_i32 s2, 0x1fee
	v_mov_b32_e32 v124, v113
	v_mov_b32_e32 v125, v115
	v_mov_b32_e32 v120, v112
	v_mov_b32_e32 v121, v114
	v_pk_mul_f32 v[122:123], v[122:123], v[124:125]
	s_nop 0
	v_pk_fma_f32 v[118:119], v[118:119], v[120:121], v[122:123] neg_lo:[0,0,1] neg_hi:[0,0,1]
	v_mov_b32_e32 v120, v113
	v_pk_mul_f32 v[118:119], v[132:133], v[118:119] op_sel_hi:[0,1]
	v_cvt_pk_bf16_f32 v118, v118, v119
	v_mov_b32_e32 v122, v108
	v_mov_b32_e32 v123, v96
	v_mov_b32_e32 v113, v115
	global_store_dword v[116:117], v118, off
	v_mov_b32_e32 v118, v100
	v_mov_b32_e32 v119, v104
	v_pk_mul_f32 v[112:113], v[122:123], v[112:113]
	v_cndmask_b32_e32 v100, v139, v140, vcc
	v_pk_fma_f32 v[112:113], v[118:119], v[120:121], v[112:113]
	v_mov_b32_e32 v104, v109
	v_pk_mul_f32 v[112:113], v[132:133], v[112:113] op_sel_hi:[0,1]
	v_cvt_pk_bf16_f32 v96, v112, v113
	global_store_dword v[116:117], v96, off offset:128
	v_add_u32_e32 v96, 17, v130
	v_and_b32_e32 v100, v100, v96
	v_mad_i64_i32 v[116:117], s[64:65], v96, s9, v[134:135]
	v_lshl_or_b32 v96, v100, 9, v128
	s_waitcnt vmcnt(20)
	v_mov_b32_e32 v112, v198
	v_mov_b32_e32 v113, v199
	v_mov_b32_e32 v114, v200
	v_mov_b32_e32 v115, v201
	v_mov_b32_e32 v96, v101
	v_cmp_gt_i32_e32 vcc, s2, v130
	v_mov_b32_e32 v108, v110
	s_movk_i32 s2, 0x1fed
	v_mov_b32_e32 v120, v113
	v_mov_b32_e32 v121, v115
	v_mov_b32_e32 v118, v112
	v_mov_b32_e32 v119, v114
	v_pk_mul_f32 v[120:121], v[104:105], v[120:121]
	v_mov_b32_e32 v100, v113
	v_pk_fma_f32 v[118:119], v[96:97], v[118:119], v[120:121] neg_lo:[0,0,1] neg_hi:[0,0,1]
	v_mov_b32_e32 v113, v115
	v_pk_mul_f32 v[118:119], v[132:133], v[118:119] op_sel_hi:[0,1]
	v_cvt_pk_bf16_f32 v96, v118, v119
	global_store_dword v[116:117], v96, off
	v_mov_b32_e32 v96, v109
	v_mov_b32_e32 v104, v101
	v_mov_b32_e32 v101, v114
	v_pk_mul_f32 v[96:97], v[96:97], v[112:113]
	v_mov_b32_e32 v109, v106
	v_pk_fma_f32 v[96:97], v[104:105], v[100:101], v[96:97]
	v_mov_b32_e32 v101, v98
	v_pk_mul_f32 v[96:97], v[132:133], v[96:97] op_sel_hi:[0,1]
	v_cvt_pk_bf16_f32 v96, v96, v97
	global_store_dword v[116:117], v96, off offset:128
	v_add_u32_e32 v96, 18, v130
	v_cndmask_b32_e32 v97, v139, v140, vcc
	v_and_b32_e32 v100, v97, v96
	v_lshl_or_b32 v100, v100, 9, v128
	s_waitcnt vmcnt(21)
	v_mov_b32_e32 v112, v202
	v_mov_b32_e32 v113, v203
	v_mov_b32_e32 v114, v204
	v_mov_b32_e32 v115, v205
	v_mov_b32_e32 v100, v102
	v_mad_i64_i32 v[96:97], s[64:65], v96, s9, v[134:135]
	v_cmp_gt_i32_e32 vcc, s2, v130
	s_movk_i32 s2, 0x1fe0
	v_mov_b32_e32 v116, v113
	v_mov_b32_e32 v117, v115
	v_mov_b32_e32 v104, v112
	v_mov_b32_e32 v105, v114
	v_pk_mul_f32 v[108:109], v[108:109], v[116:117]
	s_nop 0
	v_pk_fma_f32 v[100:101], v[100:101], v[104:105], v[108:109] neg_lo:[0,0,1] neg_hi:[0,0,1]
	v_mov_b32_e32 v104, v113
	v_pk_mul_f32 v[100:101], v[132:133], v[100:101] op_sel_hi:[0,1]
	v_cvt_pk_bf16_f32 v100, v100, v101
	v_mov_b32_e32 v108, v110
	v_mov_b32_e32 v109, v98
	v_mov_b32_e32 v113, v115
	global_store_dword v[96:97], v100, off
	v_mov_b32_e32 v100, v102
	v_mov_b32_e32 v101, v106
	v_pk_mul_f32 v[108:109], v[108:109], v[112:113]
	v_mov_b32_e32 v106, v111
	v_pk_fma_f32 v[100:101], v[100:101], v[104:105], v[108:109]
	v_mov_b32_e32 v102, v84
	v_pk_mul_f32 v[100:101], v[132:133], v[100:101] op_sel_hi:[0,1]
	v_cvt_pk_bf16_f32 v98, v100, v101
	global_store_dword v[96:97], v98, off offset:128
	v_add_u32_e32 v96, 19, v130
	v_cndmask_b32_e32 v97, v139, v140, vcc
	v_and_b32_e32 v98, v97, v96
	v_lshl_or_b32 v98, v98, 9, v128
	s_waitcnt vmcnt(22)
; #define EPI_FENCE(j) do { if ((j) == 0) asm volatile("" ::: "memory"); } while (0)
; __device__ __forceinline__ void phase_gemm1(const Params& p, int wid_s, char* shm) {
;     ...
;       for (int ai = 0; ai < 2; ++ai)
; #pragma unroll
;         for (int m = 0; m < 4; ++m)
; #pragma unroll
;           for (int j = 0; j < 4; ++j) { EPI_FENCE(j);
;             int tok = tokbase + ai * 128 + m * 16 + j;
;             int t = tok < 8192 ? (tok & 2047) : (tok & 4095);
;             u16* drow = dst + (size_t)tok * 1536 + hh * 128 + d;
;             float4 cs = *(const float4*)(rope + (t * 64 + d) * 2);
;             float a0 = acc[ai][0][m][0][j], a1 = acc[ai][0][m][1][j], b0 = acc[ai][1][m][0][j], b1 = acc[ai][1][m][1][j];
;             *(unsigned*)(drow) = pack2((a0 * cs.x - b0 * cs.y) * scl, (a1 * cs.z - b1 * cs.w) * scl);
;             *(unsigned*)(drow + 64) = pack2((b0 * cs.x + a0 * cs.y) * scl, (b1 * cs.z + a1 * cs.w) * scl);
	v_mov_b32_e32 v112, v206
	v_mov_b32_e32 v113, v207
	v_mov_b32_e32 v114, v208
	v_mov_b32_e32 v115, v209
	v_mov_b32_e32 v98, v103
	v_mad_i64_i32 v[96:97], s[64:65], v96, s9, v[134:135]
	v_cmp_gt_i32_e32 vcc, s2, v130
	s_movk_i32 s2, 0x1fdf
	v_mov_b32_e32 v104, v113
	v_mov_b32_e32 v105, v115
	v_mov_b32_e32 v100, v112
	v_mov_b32_e32 v101, v114
	v_pk_mul_f32 v[104:105], v[106:107], v[104:105]
	v_mov_b32_e32 v106, v103
	v_pk_fma_f32 v[100:101], v[98:99], v[100:101], v[104:105] neg_lo:[0,0,1] neg_hi:[0,0,1]
	v_mov_b32_e32 v103, v80
	v_pk_mul_f32 v[100:101], v[132:133], v[100:101] op_sel_hi:[0,1]
	v_cvt_pk_bf16_f32 v98, v100, v101
	global_store_dword v[96:97], v98, off
	v_mov_b32_e32 v100, v113
	v_mov_b32_e32 v98, v111
	v_mov_b32_e32 v113, v115
	v_mov_b32_e32 v101, v114
	v_pk_mul_f32 v[98:99], v[98:99], v[112:113]
	s_nop 0
	v_pk_fma_f32 v[98:99], v[106:107], v[100:101], v[98:99]
	v_mov_b32_e32 v106, v92
	v_pk_mul_f32 v[98:99], v[132:133], v[98:99] op_sel_hi:[0,1]
	v_cvt_pk_bf16_f32 v98, v98, v99
	global_store_dword v[96:97], v98, off offset:128
	v_add_u32_e32 v96, 32, v130
	v_cndmask_b32_e32 v97, v139, v140, vcc
	v_and_b32_e32 v97, v97, v96
	v_mad_i64_i32 v[100:101], s[64:65], v96, s9, v[134:135]
	v_lshl_or_b32 v96, v97, 9, v128
	s_waitcnt vmcnt(23)
	v_mov_b32_e32 v96, v210
	v_mov_b32_e32 v97, v211
	v_mov_b32_e32 v98, v212
	v_mov_b32_e32 v99, v213
	v_mov_b32_e32 v107, v88
	v_cmp_gt_i32_e32 vcc, s2, v130
	s_movk_i32 s2, 0x1fde
	v_mov_b32_e32 v108, v97
	v_mov_b32_e32 v109, v99
	v_mov_b32_e32 v104, v96
	v_mov_b32_e32 v105, v98
	v_pk_mul_f32 v[106:107], v[106:107], v[108:109]
	s_nop 0
	v_pk_fma_f32 v[102:103], v[102:103], v[104:105], v[106:107] neg_lo:[0,0,1] neg_hi:[0,0,1]
	v_mov_b32_e32 v104, v97
	v_pk_mul_f32 v[102:103], v[132:133], v[102:103] op_sel_hi:[0,1]
	v_cvt_pk_bf16_f32 v102, v102, v103
	v_mov_b32_e32 v106, v92
	v_mov_b32_e32 v107, v80
	v_mov_b32_e32 v97, v99
	global_store_dword v[100:101], v102, off
	v_mov_b32_e32 v102, v84
	v_mov_b32_e32 v103, v88
	v_pk_mul_f32 v[96:97], v[106:107], v[96:97]
	v_cndmask_b32_e32 v84, v139, v140, vcc
	v_pk_fma_f32 v[96:97], v[102:103], v[104:105], v[96:97]
	v_mov_b32_e32 v88, v93
	v_pk_mul_f32 v[96:97], v[132:133], v[96:97] op_sel_hi:[0,1]
	v_cvt_pk_bf16_f32 v80, v96, v97
	global_store_dword v[100:101], v80, off offset:128
	v_add_u32_e32 v80, 33, v130
	v_and_b32_e32 v84, v84, v80
	v_mad_i64_i32 v[100:101], s[64:65], v80, s9, v[134:135]
	v_lshl_or_b32 v80, v84, 9, v128
	s_waitcnt vmcnt(24)
	v_mov_b32_e32 v96, v214
	v_mov_b32_e32 v97, v215
	v_mov_b32_e32 v98, v216
	v_mov_b32_e32 v99, v217
	v_mov_b32_e32 v80, v85
	v_cmp_gt_i32_e32 vcc, s2, v130
	v_mov_b32_e32 v92, v94
	s_movk_i32 s2, 0x1fdd
	v_mov_b32_e32 v104, v97
	v_mov_b32_e32 v105, v99
	v_mov_b32_e32 v102, v96
	v_mov_b32_e32 v103, v98
	v_pk_mul_f32 v[104:105], v[88:89], v[104:105]
	v_mov_b32_e32 v84, v97
	v_pk_fma_f32 v[102:103], v[80:81], v[102:103], v[104:105] neg_lo:[0,0,1] neg_hi:[0,0,1]
	v_mov_b32_e32 v97, v99
	v_pk_mul_f32 v[102:103], v[132:133], v[102:103] op_sel_hi:[0,1]
	v_cvt_pk_bf16_f32 v80, v102, v103
	global_store_dword v[100:101], v80, off
	v_mov_b32_e32 v80, v93
	v_mov_b32_e32 v88, v85
	v_mov_b32_e32 v85, v98
	v_pk_mul_f32 v[80:81], v[80:81], v[96:97]
	v_mov_b32_e32 v93, v90
	v_pk_fma_f32 v[80:81], v[88:89], v[84:85], v[80:81]
	v_mov_b32_e32 v85, v82
	v_pk_mul_f32 v[80:81], v[132:133], v[80:81] op_sel_hi:[0,1]
	v_cvt_pk_bf16_f32 v80, v80, v81
	global_store_dword v[100:101], v80, off offset:128
	v_add_u32_e32 v80, 34, v130
	v_cndmask_b32_e32 v81, v139, v140, vcc
	v_and_b32_e32 v84, v81, v80
	v_lshl_or_b32 v84, v84, 9, v128
	s_waitcnt vmcnt(25)
	v_mov_b32_e32 v96, v218
	v_mov_b32_e32 v97, v219
	v_mov_b32_e32 v98, v220
	v_mov_b32_e32 v99, v221
	v_mov_b32_e32 v84, v86
	v_mad_i64_i32 v[80:81], s[64:65], v80, s9, v[134:135]
	v_cmp_gt_i32_e32 vcc, s2, v130
	s_movk_i32 s2, 0x1fd0
	v_mov_b32_e32 v100, v97
	v_mov_b32_e32 v101, v99
	v_mov_b32_e32 v88, v96
	v_mov_b32_e32 v89, v98
	v_pk_mul_f32 v[92:93], v[92:93], v[100:101]
	s_nop 0
	v_pk_fma_f32 v[84:85], v[84:85], v[88:89], v[92:93] neg_lo:[0,0,1] neg_hi:[0,0,1]
	v_mov_b32_e32 v88, v97
	v_pk_mul_f32 v[84:85], v[132:133], v[84:85] op_sel_hi:[0,1]
	v_cvt_pk_bf16_f32 v84, v84, v85
	v_mov_b32_e32 v92, v94
	v_mov_b32_e32 v93, v82
	v_mov_b32_e32 v97, v99
	global_store_dword v[80:81], v84, off
	v_mov_b32_e32 v84, v86
	v_mov_b32_e32 v85, v90
	v_pk_mul_f32 v[92:93], v[92:93], v[96:97]
	v_mov_b32_e32 v90, v95
	v_pk_fma_f32 v[84:85], v[84:85], v[88:89], v[92:93]
	v_mov_b32_e32 v86, v68
	v_pk_mul_f32 v[84:85], v[132:133], v[84:85] op_sel_hi:[0,1]
	v_cvt_pk_bf16_f32 v82, v84, v85
	global_store_dword v[80:81], v82, off offset:128
	v_add_u32_e32 v80, 35, v130
	v_cndmask_b32_e32 v81, v139, v140, vcc
	v_and_b32_e32 v82, v81, v80
	v_lshl_or_b32 v82, v82, 9, v128
	s_waitcnt vmcnt(26)
	v_mov_b32_e32 v96, v222
	v_mov_b32_e32 v97, v223
	v_mov_b32_e32 v98, v224
	v_mov_b32_e32 v99, v225
	v_mov_b32_e32 v82, v87
	v_mad_i64_i32 v[80:81], s[64:65], v80, s9, v[134:135]
	v_cmp_gt_i32_e32 vcc, s2, v130
	s_movk_i32 s2, 0x1fcf
	v_mov_b32_e32 v88, v97
	v_mov_b32_e32 v89, v99
	v_mov_b32_e32 v84, v96
	v_mov_b32_e32 v85, v98
	v_pk_mul_f32 v[88:89], v[90:91], v[88:89]
	v_mov_b32_e32 v90, v87
	v_pk_fma_f32 v[84:85], v[82:83], v[84:85], v[88:89] neg_lo:[0,0,1] neg_hi:[0,0,1]
	v_mov_b32_e32 v87, v64
	v_pk_mul_f32 v[84:85], v[132:133], v[84:85] op_sel_hi:[0,1]
	v_cvt_pk_bf16_f32 v82, v84, v85
	global_store_dword v[80:81], v82, off
	v_mov_b32_e32 v84, v97
	v_mov_b32_e32 v82, v95
	v_mov_b32_e32 v97, v99
	v_mov_b32_e32 v85, v98
	v_pk_mul_f32 v[82:83], v[82:83], v[96:97]
	s_nop 0
	v_pk_fma_f32 v[82:83], v[90:91], v[84:85], v[82:83]
	v_mov_b32_e32 v90, v76
	v_pk_mul_f32 v[82:83], v[132:133], v[82:83] op_sel_hi:[0,1]
	v_cvt_pk_bf16_f32 v82, v82, v83
	global_store_dword v[80:81], v82, off offset:128
	v_add_u32_e32 v80, 48, v130
	v_cndmask_b32_e32 v81, v139, v140, vcc
	v_and_b32_e32 v81, v81, v80
	v_mad_i64_i32 v[84:85], s[64:65], v80, s9, v[134:135]
	v_lshl_or_b32 v80, v81, 9, v128
	s_waitcnt vmcnt(27)
; #define EPI_FENCE(j) do { if ((j) == 0) asm volatile("" ::: "memory"); } while (0)
; __device__ __forceinline__ void phase_gemm1(const Params& p, int wid_s, char* shm) {
;     ...
;       for (int ai = 0; ai < 2; ++ai)
; #pragma unroll
;         for (int m = 0; m < 4; ++m)
; #pragma unroll
;           for (int j = 0; j < 4; ++j) { EPI_FENCE(j);
;             int tok = tokbase + ai * 128 + m * 16 + j;
;             int t = tok < 8192 ? (tok & 2047) : (tok & 4095);
;             u16* drow = dst + (size_t)tok * 1536 + hh * 128 + d;
;             float4 cs = *(const float4*)(rope + (t * 64 + d) * 2);
;             float a0 = acc[ai][0][m][0][j], a1 = acc[ai][0][m][1][j], b0 = acc[ai][1][m][0][j], b1 = acc[ai][1][m][1][j];
;             *(unsigned*)(drow) = pack2((a0 * cs.x - b0 * cs.y) * scl, (a1 * cs.z - b1 * cs.w) * scl);
;             *(unsigned*)(drow + 64) = pack2((b0 * cs.x + a0 * cs.y) * scl, (b1 * cs.z + a1 * cs.w) * scl);
	v_mov_b32_e32 v80, v226
	v_mov_b32_e32 v81, v227
	v_mov_b32_e32 v82, v228
	v_mov_b32_e32 v83, v229
	v_mov_b32_e32 v91, v72
	v_cmp_gt_i32_e32 vcc, s2, v130
	s_movk_i32 s2, 0x1fce
	v_mov_b32_e32 v92, v81
	v_mov_b32_e32 v93, v83
	v_mov_b32_e32 v88, v80
	v_mov_b32_e32 v89, v82
	v_pk_mul_f32 v[90:91], v[90:91], v[92:93]
	s_nop 0
	v_pk_fma_f32 v[86:87], v[86:87], v[88:89], v[90:91] neg_lo:[0,0,1] neg_hi:[0,0,1]
	v_mov_b32_e32 v88, v81
	v_pk_mul_f32 v[86:87], v[132:133], v[86:87] op_sel_hi:[0,1]
	v_cvt_pk_bf16_f32 v86, v86, v87
	v_mov_b32_e32 v90, v76
	v_mov_b32_e32 v91, v64
	v_mov_b32_e32 v81, v83
	global_store_dword v[84:85], v86, off
	v_mov_b32_e32 v86, v68
	v_mov_b32_e32 v87, v72
	v_pk_mul_f32 v[80:81], v[90:91], v[80:81]
	v_cndmask_b32_e32 v68, v139, v140, vcc
	v_pk_fma_f32 v[80:81], v[86:87], v[88:89], v[80:81]
	v_mov_b32_e32 v72, v77
	v_pk_mul_f32 v[80:81], v[132:133], v[80:81] op_sel_hi:[0,1]
	v_cvt_pk_bf16_f32 v64, v80, v81
	global_store_dword v[84:85], v64, off offset:128
	v_add_u32_e32 v64, 49, v130
	v_and_b32_e32 v68, v68, v64
	v_mad_i64_i32 v[84:85], s[64:65], v64, s9, v[134:135]
	v_lshl_or_b32 v64, v68, 9, v128
	s_waitcnt vmcnt(28)
	v_mov_b32_e32 v80, v230
	v_mov_b32_e32 v81, v231
	v_mov_b32_e32 v82, v232
	v_mov_b32_e32 v83, v233
	v_mov_b32_e32 v64, v69
	v_cmp_gt_i32_e32 vcc, s2, v130
	v_mov_b32_e32 v76, v78
	s_movk_i32 s2, 0x1fcd
	v_mov_b32_e32 v88, v81
	v_mov_b32_e32 v89, v83
	v_mov_b32_e32 v86, v80
	v_mov_b32_e32 v87, v82
	v_pk_mul_f32 v[88:89], v[72:73], v[88:89]
	v_mov_b32_e32 v68, v81
	v_pk_fma_f32 v[86:87], v[64:65], v[86:87], v[88:89] neg_lo:[0,0,1] neg_hi:[0,0,1]
	v_mov_b32_e32 v81, v83
	v_pk_mul_f32 v[86:87], v[132:133], v[86:87] op_sel_hi:[0,1]
	v_cvt_pk_bf16_f32 v64, v86, v87
	global_store_dword v[84:85], v64, off
	v_mov_b32_e32 v64, v77
	v_mov_b32_e32 v72, v69
	v_mov_b32_e32 v69, v82
	v_pk_mul_f32 v[64:65], v[64:65], v[80:81]
	v_mov_b32_e32 v77, v74
	v_pk_fma_f32 v[64:65], v[72:73], v[68:69], v[64:65]
	v_mov_b32_e32 v69, v66
	v_pk_mul_f32 v[64:65], v[132:133], v[64:65] op_sel_hi:[0,1]
	v_cvt_pk_bf16_f32 v64, v64, v65
	global_store_dword v[84:85], v64, off offset:128
	v_add_u32_e32 v64, 50, v130
	v_cndmask_b32_e32 v65, v139, v140, vcc
	v_and_b32_e32 v68, v65, v64
	v_lshl_or_b32 v68, v68, 9, v128
	s_waitcnt vmcnt(29)
	v_mov_b32_e32 v80, v234
	v_mov_b32_e32 v81, v235
	v_mov_b32_e32 v82, v236
	v_mov_b32_e32 v83, v237
	v_mov_b32_e32 v68, v70
	v_mad_i64_i32 v[64:65], s[64:65], v64, s9, v[134:135]
	v_cmp_gt_i32_e32 vcc, s2, v130
	s_movk_i32 s2, 0x1f80
	v_mov_b32_e32 v84, v81
	v_mov_b32_e32 v85, v83
	v_mov_b32_e32 v72, v80
	v_mov_b32_e32 v73, v82
	v_pk_mul_f32 v[76:77], v[76:77], v[84:85]
	s_nop 0
	v_pk_fma_f32 v[68:69], v[68:69], v[72:73], v[76:77] neg_lo:[0,0,1] neg_hi:[0,0,1]
	v_mov_b32_e32 v72, v81
	v_pk_mul_f32 v[68:69], v[132:133], v[68:69] op_sel_hi:[0,1]
	v_cvt_pk_bf16_f32 v68, v68, v69
	v_mov_b32_e32 v76, v78
	v_mov_b32_e32 v77, v66
	v_mov_b32_e32 v81, v83
	global_store_dword v[64:65], v68, off
	v_mov_b32_e32 v68, v70
	v_mov_b32_e32 v69, v74
	v_pk_mul_f32 v[76:77], v[76:77], v[80:81]
	v_mov_b32_e32 v74, v79
	v_pk_fma_f32 v[68:69], v[68:69], v[72:73], v[76:77]
	v_mov_b32_e32 v70, v52
	v_pk_mul_f32 v[68:69], v[132:133], v[68:69] op_sel_hi:[0,1]
	v_cvt_pk_bf16_f32 v66, v68, v69
	global_store_dword v[64:65], v66, off offset:128
	v_add_u32_e32 v64, 51, v130
	v_cndmask_b32_e32 v65, v139, v140, vcc
	v_and_b32_e32 v66, v65, v64
	v_lshl_or_b32 v66, v66, 9, v128
	s_waitcnt vmcnt(30)
	v_mov_b32_e32 v80, v238
	v_mov_b32_e32 v81, v239
	v_mov_b32_e32 v82, v240
	v_mov_b32_e32 v83, v241
	v_add_u32_e32 v242, 0x80, v130
	v_and_b32_e32 v242, v246, v242
	v_lshl_or_b32 v242, v242, 9, v128
	global_load_dwordx4 v[178:181], v242, s[4:5]
	v_add_u32_e32 v242, 0x81, v130
	v_and_b32_e32 v242, v246, v242
	v_lshl_or_b32 v242, v242, 9, v128
	global_load_dwordx4 v[182:185], v242, s[4:5]
	v_add_u32_e32 v242, 0x82, v130
	v_and_b32_e32 v242, v246, v242
	v_lshl_or_b32 v242, v242, 9, v128
	global_load_dwordx4 v[186:189], v242, s[4:5]
	v_add_u32_e32 v242, 0x83, v130
	v_and_b32_e32 v242, v246, v242
	v_lshl_or_b32 v242, v242, 9, v128
	global_load_dwordx4 v[190:193], v242, s[4:5]
	v_add_u32_e32 v242, 0x90, v130
	v_and_b32_e32 v242, v246, v242
	v_lshl_or_b32 v242, v242, 9, v128
	global_load_dwordx4 v[194:197], v242, s[4:5]
	v_add_u32_e32 v242, 0x91, v130
	v_and_b32_e32 v242, v246, v242
	v_lshl_or_b32 v242, v242, 9, v128
	global_load_dwordx4 v[198:201], v242, s[4:5]
	v_add_u32_e32 v242, 0x92, v130
	v_and_b32_e32 v242, v246, v242
	v_lshl_or_b32 v242, v242, 9, v128
	global_load_dwordx4 v[202:205], v242, s[4:5]
	v_add_u32_e32 v242, 0x93, v130
	v_and_b32_e32 v242, v246, v242
	v_lshl_or_b32 v242, v242, 9, v128
	global_load_dwordx4 v[206:209], v242, s[4:5]
	v_add_u32_e32 v242, 0xa0, v130
	v_and_b32_e32 v242, v246, v242
	v_lshl_or_b32 v242, v242, 9, v128
	global_load_dwordx4 v[210:213], v242, s[4:5]
	v_add_u32_e32 v242, 0xa1, v130
	v_and_b32_e32 v242, v246, v242
	v_lshl_or_b32 v242, v242, 9, v128
	global_load_dwordx4 v[214:217], v242, s[4:5]
	v_add_u32_e32 v242, 0xa2, v130
	v_and_b32_e32 v242, v246, v242
	v_lshl_or_b32 v242, v242, 9, v128
	global_load_dwordx4 v[218:221], v242, s[4:5]
	v_add_u32_e32 v242, 0xa3, v130
	v_and_b32_e32 v242, v246, v242
	v_lshl_or_b32 v242, v242, 9, v128
	global_load_dwordx4 v[222:225], v242, s[4:5]
	v_add_u32_e32 v242, 0xb0, v130
	v_and_b32_e32 v242, v246, v242
	v_lshl_or_b32 v242, v242, 9, v128
	global_load_dwordx4 v[226:229], v242, s[4:5]
	v_add_u32_e32 v242, 0xb1, v130
	v_and_b32_e32 v242, v246, v242
	v_lshl_or_b32 v242, v242, 9, v128
	global_load_dwordx4 v[230:233], v242, s[4:5]
	v_add_u32_e32 v242, 0xb2, v130
	v_and_b32_e32 v242, v246, v242
	v_lshl_or_b32 v242, v242, 9, v128
	global_load_dwordx4 v[234:237], v242, s[4:5]
	v_add_u32_e32 v242, 0xb3, v130
	v_and_b32_e32 v242, v246, v242
	v_lshl_or_b32 v242, v242, 9, v128
	global_load_dwordx4 v[238:241], v242, s[4:5]
	v_mov_b32_e32 v66, v71
	v_mad_i64_i32 v[64:65], s[64:65], v64, s9, v[134:135]
	v_cmp_gt_i32_e32 vcc, s2, v130
	s_movk_i32 s2, 0x1f7f
	v_mov_b32_e32 v72, v81
	v_mov_b32_e32 v73, v83
	v_mov_b32_e32 v68, v80
	v_mov_b32_e32 v69, v82
	v_pk_mul_f32 v[72:73], v[74:75], v[72:73]
	v_mov_b32_e32 v74, v71
	v_pk_fma_f32 v[68:69], v[66:67], v[68:69], v[72:73] neg_lo:[0,0,1] neg_hi:[0,0,1]
	v_mov_b32_e32 v71, v48
	v_pk_mul_f32 v[68:69], v[132:133], v[68:69] op_sel_hi:[0,1]
	v_cvt_pk_bf16_f32 v66, v68, v69
	global_store_dword v[64:65], v66, off
	v_mov_b32_e32 v68, v81
	v_mov_b32_e32 v66, v79
	v_mov_b32_e32 v81, v83
	v_mov_b32_e32 v69, v82
	v_pk_mul_f32 v[66:67], v[66:67], v[80:81]
	s_nop 0
	v_pk_fma_f32 v[66:67], v[74:75], v[68:69], v[66:67]
	v_mov_b32_e32 v74, v60
	v_pk_mul_f32 v[66:67], v[132:133], v[66:67] op_sel_hi:[0,1]
	v_cvt_pk_bf16_f32 v66, v66, v67
	global_store_dword v[64:65], v66, off offset:128
	v_add_u32_e32 v64, 0x80, v130
	v_cndmask_b32_e32 v65, v139, v140, vcc
	v_and_b32_e32 v65, v65, v64
	v_mad_i64_i32 v[68:69], s[64:65], v64, s9, v[134:135]
	v_lshl_or_b32 v64, v65, 9, v128
	s_waitcnt vmcnt(17)
; #define EPI_FENCE(j) do { if ((j) == 0) asm volatile("" ::: "memory"); } while (0)
; __device__ __forceinline__ void phase_gemm1(const Params& p, int wid_s, char* shm) {
;     ...
;       for (int ai = 0; ai < 2; ++ai)
; #pragma unroll
;         for (int m = 0; m < 4; ++m)
; #pragma unroll
;           for (int j = 0; j < 4; ++j) { EPI_FENCE(j);
;             int tok = tokbase + ai * 128 + m * 16 + j;
;             int t = tok < 8192 ? (tok & 2047) : (tok & 4095);
;             u16* drow = dst + (size_t)tok * 1536 + hh * 128 + d;
;             float4 cs = *(const float4*)(rope + (t * 64 + d) * 2);
;             float a0 = acc[ai][0][m][0][j], a1 = acc[ai][0][m][1][j], b0 = acc[ai][1][m][0][j], b1 = acc[ai][1][m][1][j];
;             *(unsigned*)(drow) = pack2((a0 * cs.x - b0 * cs.y) * scl, (a1 * cs.z - b1 * cs.w) * scl);
;             *(unsigned*)(drow + 64) = pack2((b0 * cs.x + a0 * cs.y) * scl, (b1 * cs.z + a1 * cs.w) * scl);
	v_mov_b32_e32 v64, v178
	v_mov_b32_e32 v65, v179
	v_mov_b32_e32 v66, v180
	v_mov_b32_e32 v67, v181
	v_mov_b32_e32 v75, v56
	v_cmp_gt_i32_e32 vcc, s2, v130
	s_movk_i32 s2, 0x1f7e
	v_mov_b32_e32 v76, v65
	v_mov_b32_e32 v77, v67
	v_mov_b32_e32 v72, v64
	v_mov_b32_e32 v73, v66
	v_pk_mul_f32 v[74:75], v[74:75], v[76:77]
	s_nop 0
	v_pk_fma_f32 v[70:71], v[70:71], v[72:73], v[74:75] neg_lo:[0,0,1] neg_hi:[0,0,1]
	v_mov_b32_e32 v72, v65
	v_pk_mul_f32 v[70:71], v[132:133], v[70:71] op_sel_hi:[0,1]
	v_cvt_pk_bf16_f32 v70, v70, v71
	v_mov_b32_e32 v74, v60
	v_mov_b32_e32 v75, v48
	v_mov_b32_e32 v65, v67
	global_store_dword v[68:69], v70, off
	v_mov_b32_e32 v70, v52
	v_mov_b32_e32 v71, v56
	v_pk_mul_f32 v[64:65], v[74:75], v[64:65]
	v_cndmask_b32_e32 v52, v139, v140, vcc
	v_pk_fma_f32 v[64:65], v[70:71], v[72:73], v[64:65]
	v_mov_b32_e32 v56, v61
	v_pk_mul_f32 v[64:65], v[132:133], v[64:65] op_sel_hi:[0,1]
	v_cvt_pk_bf16_f32 v48, v64, v65
	global_store_dword v[68:69], v48, off offset:128
	v_add_u32_e32 v48, 0x81, v130
	v_and_b32_e32 v52, v52, v48
	v_mad_i64_i32 v[68:69], s[64:65], v48, s9, v[134:135]
	v_lshl_or_b32 v48, v52, 9, v128
	s_waitcnt vmcnt(18)
	v_mov_b32_e32 v64, v182
	v_mov_b32_e32 v65, v183
	v_mov_b32_e32 v66, v184
	v_mov_b32_e32 v67, v185
	v_mov_b32_e32 v48, v53
	v_cmp_gt_i32_e32 vcc, s2, v130
	v_mov_b32_e32 v60, v62
	s_movk_i32 s2, 0x1f7d
	v_mov_b32_e32 v72, v65
	v_mov_b32_e32 v73, v67
	v_mov_b32_e32 v70, v64
	v_mov_b32_e32 v71, v66
	v_pk_mul_f32 v[72:73], v[56:57], v[72:73]
	v_mov_b32_e32 v52, v65
	v_pk_fma_f32 v[70:71], v[48:49], v[70:71], v[72:73] neg_lo:[0,0,1] neg_hi:[0,0,1]
	v_mov_b32_e32 v65, v67
	v_pk_mul_f32 v[70:71], v[132:133], v[70:71] op_sel_hi:[0,1]
	v_cvt_pk_bf16_f32 v48, v70, v71
	global_store_dword v[68:69], v48, off
	v_mov_b32_e32 v48, v61
	v_mov_b32_e32 v56, v53
	v_mov_b32_e32 v53, v66
	v_pk_mul_f32 v[48:49], v[48:49], v[64:65]
	v_mov_b32_e32 v61, v58
	v_pk_fma_f32 v[48:49], v[56:57], v[52:53], v[48:49]
	v_mov_b32_e32 v53, v50
	v_pk_mul_f32 v[48:49], v[132:133], v[48:49] op_sel_hi:[0,1]
	v_cvt_pk_bf16_f32 v48, v48, v49
	global_store_dword v[68:69], v48, off offset:128
	v_add_u32_e32 v48, 0x82, v130
	v_cndmask_b32_e32 v49, v139, v140, vcc
	v_and_b32_e32 v52, v49, v48
	v_lshl_or_b32 v52, v52, 9, v128
	s_waitcnt vmcnt(19)
	v_mov_b32_e32 v64, v186
	v_mov_b32_e32 v65, v187
	v_mov_b32_e32 v66, v188
	v_mov_b32_e32 v67, v189
	v_mov_b32_e32 v52, v54
	v_mad_i64_i32 v[48:49], s[64:65], v48, s9, v[134:135]
	v_cmp_gt_i32_e32 vcc, s2, v130
	s_movk_i32 s2, 0x1f70
	v_mov_b32_e32 v68, v65
	v_mov_b32_e32 v69, v67
	v_mov_b32_e32 v56, v64
	v_mov_b32_e32 v57, v66
	v_pk_mul_f32 v[60:61], v[60:61], v[68:69]
	s_nop 0
	v_pk_fma_f32 v[52:53], v[52:53], v[56:57], v[60:61] neg_lo:[0,0,1] neg_hi:[0,0,1]
	v_mov_b32_e32 v56, v65
	v_pk_mul_f32 v[52:53], v[132:133], v[52:53] op_sel_hi:[0,1]
	v_cvt_pk_bf16_f32 v52, v52, v53
	v_mov_b32_e32 v60, v62
	v_mov_b32_e32 v61, v50
	v_mov_b32_e32 v65, v67
	global_store_dword v[48:49], v52, off
	v_mov_b32_e32 v52, v54
	v_mov_b32_e32 v53, v58
	v_pk_mul_f32 v[60:61], v[60:61], v[64:65]
	v_mov_b32_e32 v58, v63
	v_pk_fma_f32 v[52:53], v[52:53], v[56:57], v[60:61]
	v_mov_b32_e32 v54, v36
	v_pk_mul_f32 v[52:53], v[132:133], v[52:53] op_sel_hi:[0,1]
	v_cvt_pk_bf16_f32 v50, v52, v53
	global_store_dword v[48:49], v50, off offset:128
	v_add_u32_e32 v48, 0x83, v130
	v_cndmask_b32_e32 v49, v139, v140, vcc
	v_and_b32_e32 v50, v49, v48
	v_lshl_or_b32 v50, v50, 9, v128
	s_waitcnt vmcnt(20)
	v_mov_b32_e32 v64, v190
	v_mov_b32_e32 v65, v191
	v_mov_b32_e32 v66, v192
	v_mov_b32_e32 v67, v193
	v_mov_b32_e32 v50, v55
	v_mad_i64_i32 v[48:49], s[64:65], v48, s9, v[134:135]
	v_cmp_gt_i32_e32 vcc, s2, v130
	s_movk_i32 s2, 0x1f6f
	v_mov_b32_e32 v56, v65
	v_mov_b32_e32 v57, v67
	v_mov_b32_e32 v52, v64
	v_mov_b32_e32 v53, v66
	v_pk_mul_f32 v[56:57], v[58:59], v[56:57]
	v_mov_b32_e32 v58, v55
	v_pk_fma_f32 v[52:53], v[50:51], v[52:53], v[56:57] neg_lo:[0,0,1] neg_hi:[0,0,1]
	v_mov_b32_e32 v55, v32
	v_pk_mul_f32 v[52:53], v[132:133], v[52:53] op_sel_hi:[0,1]
	v_cvt_pk_bf16_f32 v50, v52, v53
	global_store_dword v[48:49], v50, off
	v_mov_b32_e32 v52, v65
	v_mov_b32_e32 v50, v63
	v_mov_b32_e32 v65, v67
	v_mov_b32_e32 v53, v66
	v_pk_mul_f32 v[50:51], v[50:51], v[64:65]
	s_nop 0
	v_pk_fma_f32 v[50:51], v[58:59], v[52:53], v[50:51]
	v_mov_b32_e32 v58, v44
	v_pk_mul_f32 v[50:51], v[132:133], v[50:51] op_sel_hi:[0,1]
	v_cvt_pk_bf16_f32 v50, v50, v51
	global_store_dword v[48:49], v50, off offset:128
	v_add_u32_e32 v48, 0x90, v130
	v_cndmask_b32_e32 v49, v139, v140, vcc
	v_and_b32_e32 v49, v49, v48
	v_mad_i64_i32 v[52:53], s[64:65], v48, s9, v[134:135]
	v_lshl_or_b32 v48, v49, 9, v128
	s_waitcnt vmcnt(21)
	v_mov_b32_e32 v48, v194
	v_mov_b32_e32 v49, v195
	v_mov_b32_e32 v50, v196
	v_mov_b32_e32 v51, v197
	v_mov_b32_e32 v59, v40
	v_cmp_gt_i32_e32 vcc, s2, v130
	s_movk_i32 s2, 0x1f6e
	v_mov_b32_e32 v60, v49
	v_mov_b32_e32 v61, v51
	v_mov_b32_e32 v56, v48
	v_mov_b32_e32 v57, v50
	v_pk_mul_f32 v[58:59], v[58:59], v[60:61]
	s_nop 0
	v_pk_fma_f32 v[54:55], v[54:55], v[56:57], v[58:59] neg_lo:[0,0,1] neg_hi:[0,0,1]
	v_mov_b32_e32 v56, v49
	v_pk_mul_f32 v[54:55], v[132:133], v[54:55] op_sel_hi:[0,1]
	v_cvt_pk_bf16_f32 v54, v54, v55
	v_mov_b32_e32 v58, v44
	v_mov_b32_e32 v59, v32
	v_mov_b32_e32 v49, v51
	global_store_dword v[52:53], v54, off
	v_mov_b32_e32 v54, v36
	v_mov_b32_e32 v55, v40
	v_pk_mul_f32 v[48:49], v[58:59], v[48:49]
	v_cndmask_b32_e32 v36, v139, v140, vcc
	v_pk_fma_f32 v[48:49], v[54:55], v[56:57], v[48:49]
	v_mov_b32_e32 v40, v45
	v_pk_mul_f32 v[48:49], v[132:133], v[48:49] op_sel_hi:[0,1]
	v_cvt_pk_bf16_f32 v32, v48, v49
	global_store_dword v[52:53], v32, off offset:128
	v_add_u32_e32 v32, 0x91, v130
	v_and_b32_e32 v36, v36, v32
	v_mad_i64_i32 v[52:53], s[64:65], v32, s9, v[134:135]
	v_lshl_or_b32 v32, v36, 9, v128
	s_waitcnt vmcnt(22)
; #define EPI_FENCE(j) do { if ((j) == 0) asm volatile("" ::: "memory"); } while (0)
; __device__ __forceinline__ void phase_gemm1(const Params& p, int wid_s, char* shm) {
;     ...
;       for (int ai = 0; ai < 2; ++ai)
; #pragma unroll
;         for (int m = 0; m < 4; ++m)
; #pragma unroll
;           for (int j = 0; j < 4; ++j) { EPI_FENCE(j);
;             int tok = tokbase + ai * 128 + m * 16 + j;
;             int t = tok < 8192 ? (tok & 2047) : (tok & 4095);
;             u16* drow = dst + (size_t)tok * 1536 + hh * 128 + d;
;             float4 cs = *(const float4*)(rope + (t * 64 + d) * 2);
;             float a0 = acc[ai][0][m][0][j], a1 = acc[ai][0][m][1][j], b0 = acc[ai][1][m][0][j], b1 = acc[ai][1][m][1][j];
;             *(unsigned*)(drow) = pack2((a0 * cs.x - b0 * cs.y) * scl, (a1 * cs.z - b1 * cs.w) * scl);
;             *(unsigned*)(drow + 64) = pack2((b0 * cs.x + a0 * cs.y) * scl, (b1 * cs.z + a1 * cs.w) * scl);
	v_mov_b32_e32 v48, v198
	v_mov_b32_e32 v49, v199
	v_mov_b32_e32 v50, v200
	v_mov_b32_e32 v51, v201
	v_mov_b32_e32 v32, v37
	v_cmp_gt_i32_e32 vcc, s2, v130
	v_mov_b32_e32 v44, v46
	s_movk_i32 s2, 0x1f6d
	v_mov_b32_e32 v56, v49
	v_mov_b32_e32 v57, v51
	v_mov_b32_e32 v54, v48
	v_mov_b32_e32 v55, v50
	v_pk_mul_f32 v[56:57], v[40:41], v[56:57]
	v_mov_b32_e32 v36, v49
	v_pk_fma_f32 v[54:55], v[32:33], v[54:55], v[56:57] neg_lo:[0,0,1] neg_hi:[0,0,1]
	v_mov_b32_e32 v49, v51
	v_pk_mul_f32 v[54:55], v[132:133], v[54:55] op_sel_hi:[0,1]
	v_cvt_pk_bf16_f32 v32, v54, v55
	global_store_dword v[52:53], v32, off
	v_mov_b32_e32 v32, v45
	v_mov_b32_e32 v40, v37
	v_mov_b32_e32 v37, v50
	v_pk_mul_f32 v[32:33], v[32:33], v[48:49]
	v_mov_b32_e32 v45, v42
	v_pk_fma_f32 v[32:33], v[40:41], v[36:37], v[32:33]
	v_mov_b32_e32 v37, v34
	v_pk_mul_f32 v[32:33], v[132:133], v[32:33] op_sel_hi:[0,1]
	v_cvt_pk_bf16_f32 v32, v32, v33
	global_store_dword v[52:53], v32, off offset:128
	v_add_u32_e32 v32, 0x92, v130
	v_cndmask_b32_e32 v33, v139, v140, vcc
	v_and_b32_e32 v36, v33, v32
	v_lshl_or_b32 v36, v36, 9, v128
	s_waitcnt vmcnt(23)
	v_mov_b32_e32 v48, v202
	v_mov_b32_e32 v49, v203
	v_mov_b32_e32 v50, v204
	v_mov_b32_e32 v51, v205
	v_mov_b32_e32 v36, v38
	v_mad_i64_i32 v[32:33], s[64:65], v32, s9, v[134:135]
	v_cmp_gt_i32_e32 vcc, s2, v130
	s_movk_i32 s2, 0x1f60
	v_mov_b32_e32 v52, v49
	v_mov_b32_e32 v53, v51
	v_mov_b32_e32 v40, v48
	v_mov_b32_e32 v41, v50
	v_pk_mul_f32 v[44:45], v[44:45], v[52:53]
	s_nop 0
	v_pk_fma_f32 v[36:37], v[36:37], v[40:41], v[44:45] neg_lo:[0,0,1] neg_hi:[0,0,1]
	v_mov_b32_e32 v40, v49
	v_pk_mul_f32 v[36:37], v[132:133], v[36:37] op_sel_hi:[0,1]
	v_cvt_pk_bf16_f32 v36, v36, v37
	v_mov_b32_e32 v44, v46
	v_mov_b32_e32 v45, v34
	v_mov_b32_e32 v49, v51
	global_store_dword v[32:33], v36, off
	v_mov_b32_e32 v36, v38
	v_mov_b32_e32 v37, v42
	v_pk_mul_f32 v[44:45], v[44:45], v[48:49]
	v_mov_b32_e32 v42, v47
	v_pk_fma_f32 v[36:37], v[36:37], v[40:41], v[44:45]
	v_mov_b32_e32 v38, v20
	v_pk_mul_f32 v[36:37], v[132:133], v[36:37] op_sel_hi:[0,1]
	v_cvt_pk_bf16_f32 v34, v36, v37
	global_store_dword v[32:33], v34, off offset:128
	v_add_u32_e32 v32, 0x93, v130
	v_cndmask_b32_e32 v33, v139, v140, vcc
	v_and_b32_e32 v34, v33, v32
	v_lshl_or_b32 v34, v34, 9, v128
	s_waitcnt vmcnt(24)
	v_mov_b32_e32 v48, v206
	v_mov_b32_e32 v49, v207
	v_mov_b32_e32 v50, v208
	v_mov_b32_e32 v51, v209
	v_mov_b32_e32 v34, v39
	v_mad_i64_i32 v[32:33], s[64:65], v32, s9, v[134:135]
	v_cmp_gt_i32_e32 vcc, s2, v130
	s_movk_i32 s2, 0x1f5f
	v_mov_b32_e32 v40, v49
	v_mov_b32_e32 v41, v51
	v_mov_b32_e32 v36, v48
	v_mov_b32_e32 v37, v50
	v_pk_mul_f32 v[40:41], v[42:43], v[40:41]
	v_mov_b32_e32 v42, v39
	v_pk_fma_f32 v[36:37], v[34:35], v[36:37], v[40:41] neg_lo:[0,0,1] neg_hi:[0,0,1]
	v_mov_b32_e32 v39, v16
	v_pk_mul_f32 v[36:37], v[132:133], v[36:37] op_sel_hi:[0,1]
	v_cvt_pk_bf16_f32 v34, v36, v37
	global_store_dword v[32:33], v34, off
	v_mov_b32_e32 v36, v49
	v_mov_b32_e32 v34, v47
	v_mov_b32_e32 v49, v51
	v_mov_b32_e32 v37, v50
	v_pk_mul_f32 v[34:35], v[34:35], v[48:49]
	s_nop 0
	v_pk_fma_f32 v[34:35], v[42:43], v[36:37], v[34:35]
	v_mov_b32_e32 v42, v28
	v_pk_mul_f32 v[34:35], v[132:133], v[34:35] op_sel_hi:[0,1]
	v_cvt_pk_bf16_f32 v34, v34, v35
	global_store_dword v[32:33], v34, off offset:128
	v_add_u32_e32 v32, 0xa0, v130
	v_cndmask_b32_e32 v33, v139, v140, vcc
	v_and_b32_e32 v33, v33, v32
	v_mad_i64_i32 v[36:37], s[64:65], v32, s9, v[134:135]
	v_lshl_or_b32 v32, v33, 9, v128
	s_waitcnt vmcnt(25)
	v_mov_b32_e32 v32, v210
	v_mov_b32_e32 v33, v211
	v_mov_b32_e32 v34, v212
	v_mov_b32_e32 v35, v213
	v_mov_b32_e32 v43, v24
	v_cmp_gt_i32_e32 vcc, s2, v130
	s_movk_i32 s2, 0x1f5e
	v_mov_b32_e32 v44, v33
	v_mov_b32_e32 v45, v35
	v_mov_b32_e32 v40, v32
	v_mov_b32_e32 v41, v34
	v_pk_mul_f32 v[42:43], v[42:43], v[44:45]
	s_nop 0
	v_pk_fma_f32 v[38:39], v[38:39], v[40:41], v[42:43] neg_lo:[0,0,1] neg_hi:[0,0,1]
	v_mov_b32_e32 v40, v33
	v_pk_mul_f32 v[38:39], v[132:133], v[38:39] op_sel_hi:[0,1]
	v_cvt_pk_bf16_f32 v38, v38, v39
	v_mov_b32_e32 v42, v28
	v_mov_b32_e32 v43, v16
	v_mov_b32_e32 v33, v35
	global_store_dword v[36:37], v38, off
	v_mov_b32_e32 v38, v20
	v_mov_b32_e32 v39, v24
	v_pk_mul_f32 v[32:33], v[42:43], v[32:33]
	v_cndmask_b32_e32 v20, v139, v140, vcc
	v_pk_fma_f32 v[32:33], v[38:39], v[40:41], v[32:33]
	v_mov_b32_e32 v24, v29
	v_pk_mul_f32 v[32:33], v[132:133], v[32:33] op_sel_hi:[0,1]
	v_cvt_pk_bf16_f32 v16, v32, v33
	global_store_dword v[36:37], v16, off offset:128
	v_add_u32_e32 v16, 0xa1, v130
	v_and_b32_e32 v20, v20, v16
	v_mad_i64_i32 v[36:37], s[64:65], v16, s9, v[134:135]
	v_lshl_or_b32 v16, v20, 9, v128
	s_waitcnt vmcnt(26)
	v_mov_b32_e32 v32, v214
	v_mov_b32_e32 v33, v215
	v_mov_b32_e32 v34, v216
	v_mov_b32_e32 v35, v217
	v_mov_b32_e32 v16, v21
	v_cmp_gt_i32_e32 vcc, s2, v130
	v_mov_b32_e32 v28, v30
	s_movk_i32 s2, 0x1f5d
	v_mov_b32_e32 v40, v33
	v_mov_b32_e32 v41, v35
	v_mov_b32_e32 v38, v32
	v_mov_b32_e32 v39, v34
	v_pk_mul_f32 v[40:41], v[24:25], v[40:41]
	v_mov_b32_e32 v20, v33
	v_pk_fma_f32 v[38:39], v[16:17], v[38:39], v[40:41] neg_lo:[0,0,1] neg_hi:[0,0,1]
	v_mov_b32_e32 v33, v35
	v_pk_mul_f32 v[38:39], v[132:133], v[38:39] op_sel_hi:[0,1]
	v_cvt_pk_bf16_f32 v16, v38, v39
	global_store_dword v[36:37], v16, off
	v_mov_b32_e32 v16, v29
	v_mov_b32_e32 v24, v21
	v_mov_b32_e32 v21, v34
	v_pk_mul_f32 v[16:17], v[16:17], v[32:33]
	v_mov_b32_e32 v29, v26
	v_pk_fma_f32 v[16:17], v[24:25], v[20:21], v[16:17]
	v_mov_b32_e32 v21, v18
	v_pk_mul_f32 v[16:17], v[132:133], v[16:17] op_sel_hi:[0,1]
	v_cvt_pk_bf16_f32 v16, v16, v17
	global_store_dword v[36:37], v16, off offset:128
	v_add_u32_e32 v16, 0xa2, v130
	v_cndmask_b32_e32 v17, v139, v140, vcc
	v_and_b32_e32 v20, v17, v16
	v_lshl_or_b32 v20, v20, 9, v128
	s_waitcnt vmcnt(27)
; #define EPI_FENCE(j) do { if ((j) == 0) asm volatile("" ::: "memory"); } while (0)
; __device__ __forceinline__ void phase_gemm1(const Params& p, int wid_s, char* shm) {
;     ...
;       for (int ai = 0; ai < 2; ++ai)
; #pragma unroll
;         for (int m = 0; m < 4; ++m)
; #pragma unroll
;           for (int j = 0; j < 4; ++j) { EPI_FENCE(j);
;             int tok = tokbase + ai * 128 + m * 16 + j;
;             int t = tok < 8192 ? (tok & 2047) : (tok & 4095);
;             u16* drow = dst + (size_t)tok * 1536 + hh * 128 + d;
;             float4 cs = *(const float4*)(rope + (t * 64 + d) * 2);
;             float a0 = acc[ai][0][m][0][j], a1 = acc[ai][0][m][1][j], b0 = acc[ai][1][m][0][j], b1 = acc[ai][1][m][1][j];
;             *(unsigned*)(drow) = pack2((a0 * cs.x - b0 * cs.y) * scl, (a1 * cs.z - b1 * cs.w) * scl);
;             *(unsigned*)(drow + 64) = pack2((b0 * cs.x + a0 * cs.y) * scl, (b1 * cs.z + a1 * cs.w) * scl);
	v_mov_b32_e32 v32, v218
	v_mov_b32_e32 v33, v219
	v_mov_b32_e32 v34, v220
	v_mov_b32_e32 v35, v221
	v_mov_b32_e32 v20, v22
	v_mad_i64_i32 v[16:17], s[64:65], v16, s9, v[134:135]
	v_cmp_gt_i32_e32 vcc, s2, v130
	s_movk_i32 s2, 0x1f50
	v_mov_b32_e32 v36, v33
	v_mov_b32_e32 v37, v35
	v_mov_b32_e32 v24, v32
	v_mov_b32_e32 v25, v34
	v_pk_mul_f32 v[28:29], v[28:29], v[36:37]
	s_nop 0
	v_pk_fma_f32 v[20:21], v[20:21], v[24:25], v[28:29] neg_lo:[0,0,1] neg_hi:[0,0,1]
	v_mov_b32_e32 v24, v33
	v_pk_mul_f32 v[20:21], v[132:133], v[20:21] op_sel_hi:[0,1]
	v_cvt_pk_bf16_f32 v20, v20, v21
	v_mov_b32_e32 v28, v30
	v_mov_b32_e32 v29, v18
	v_mov_b32_e32 v33, v35
	global_store_dword v[16:17], v20, off
	v_mov_b32_e32 v20, v22
	v_mov_b32_e32 v21, v26
	v_pk_mul_f32 v[28:29], v[28:29], v[32:33]
	v_mov_b32_e32 v26, v31
	v_pk_fma_f32 v[20:21], v[20:21], v[24:25], v[28:29]
	v_mov_b32_e32 v22, v12
	v_pk_mul_f32 v[20:21], v[132:133], v[20:21] op_sel_hi:[0,1]
	v_cvt_pk_bf16_f32 v18, v20, v21
	global_store_dword v[16:17], v18, off offset:128
	v_add_u32_e32 v16, 0xa3, v130
	v_cndmask_b32_e32 v17, v139, v140, vcc
	v_and_b32_e32 v18, v17, v16
	v_lshl_or_b32 v18, v18, 9, v128
	s_waitcnt vmcnt(28)
	v_mov_b32_e32 v32, v222
	v_mov_b32_e32 v33, v223
	v_mov_b32_e32 v34, v224
	v_mov_b32_e32 v35, v225
	v_mov_b32_e32 v18, v23
	v_mad_i64_i32 v[16:17], s[64:65], v16, s9, v[134:135]
	v_cmp_gt_i32_e32 vcc, s2, v130
	s_movk_i32 s2, 0x1f4f
	v_mov_b32_e32 v24, v33
	v_mov_b32_e32 v25, v35
	v_mov_b32_e32 v20, v32
	v_mov_b32_e32 v21, v34
	v_pk_mul_f32 v[24:25], v[26:27], v[24:25]
	v_mov_b32_e32 v26, v23
	v_pk_fma_f32 v[20:21], v[18:19], v[20:21], v[24:25] neg_lo:[0,0,1] neg_hi:[0,0,1]
	v_mov_b32_e32 v23, v0
	v_pk_mul_f32 v[20:21], v[132:133], v[20:21] op_sel_hi:[0,1]
	v_cvt_pk_bf16_f32 v18, v20, v21
	global_store_dword v[16:17], v18, off
	v_mov_b32_e32 v20, v33
	v_mov_b32_e32 v18, v31
	v_mov_b32_e32 v33, v35
	v_mov_b32_e32 v21, v34
	v_pk_mul_f32 v[18:19], v[18:19], v[32:33]
	s_nop 0
	v_pk_fma_f32 v[18:19], v[26:27], v[20:21], v[18:19]
	v_mov_b32_e32 v26, v8
	v_pk_mul_f32 v[18:19], v[132:133], v[18:19] op_sel_hi:[0,1]
	v_cvt_pk_bf16_f32 v18, v18, v19
	global_store_dword v[16:17], v18, off offset:128
	v_add_u32_e32 v16, 0xb0, v130
	v_cndmask_b32_e32 v17, v139, v140, vcc
	v_and_b32_e32 v17, v17, v16
	v_mad_i64_i32 v[20:21], s[64:65], v16, s9, v[134:135]
	v_lshl_or_b32 v16, v17, 9, v128
	s_waitcnt vmcnt(29)
	v_mov_b32_e32 v16, v226
	v_mov_b32_e32 v17, v227
	v_mov_b32_e32 v18, v228
	v_mov_b32_e32 v19, v229
	v_mov_b32_e32 v27, v4
	v_cmp_gt_i32_e32 vcc, s2, v130
	s_movk_i32 s2, 0x1f4e
	v_mov_b32_e32 v28, v17
	v_mov_b32_e32 v29, v19
	v_mov_b32_e32 v24, v16
	v_mov_b32_e32 v25, v18
	v_pk_mul_f32 v[26:27], v[26:27], v[28:29]
	s_nop 0
	v_pk_fma_f32 v[22:23], v[22:23], v[24:25], v[26:27] neg_lo:[0,0,1] neg_hi:[0,0,1]
	v_mov_b32_e32 v24, v17
	v_pk_mul_f32 v[22:23], v[132:133], v[22:23] op_sel_hi:[0,1]
	v_cvt_pk_bf16_f32 v22, v22, v23
	v_mov_b32_e32 v26, v8
	v_mov_b32_e32 v27, v0
	v_mov_b32_e32 v17, v19
	global_store_dword v[20:21], v22, off
	v_mov_b32_e32 v22, v12
	v_mov_b32_e32 v23, v4
	v_pk_mul_f32 v[16:17], v[26:27], v[16:17]
	v_cndmask_b32_e32 v4, v139, v140, vcc
	v_pk_fma_f32 v[16:17], v[22:23], v[24:25], v[16:17]
	v_cmp_gt_i32_e32 vcc, s2, v130
	v_pk_mul_f32 v[16:17], v[132:133], v[16:17] op_sel_hi:[0,1]
	v_cvt_pk_bf16_f32 v0, v16, v17
	global_store_dword v[20:21], v0, off offset:128
	v_add_u32_e32 v0, 0xb1, v130
	v_and_b32_e32 v4, v4, v0
	v_mad_i64_i32 v[20:21], s[64:65], v0, s9, v[134:135]
	v_lshl_or_b32 v0, v4, 9, v128
	s_waitcnt vmcnt(30)
	v_mov_b32_e32 v16, v230
	v_mov_b32_e32 v17, v231
	v_mov_b32_e32 v18, v232
	v_mov_b32_e32 v19, v233
	v_mov_b32_e32 v4, v9
	v_mov_b32_e32 v0, v13
	s_movk_i32 s2, 0x1f4d
	v_mov_b32_e32 v24, v17
	v_mov_b32_e32 v25, v19
	v_mov_b32_e32 v22, v16
	v_mov_b32_e32 v23, v18
	v_pk_mul_f32 v[24:25], v[4:5], v[24:25]
	v_mov_b32_e32 v12, v17
	v_pk_fma_f32 v[22:23], v[0:1], v[22:23], v[24:25] neg_lo:[0,0,1] neg_hi:[0,0,1]
	v_mov_b32_e32 v17, v19
	v_pk_mul_f32 v[22:23], v[132:133], v[22:23] op_sel_hi:[0,1]
	v_cvt_pk_bf16_f32 v0, v22, v23
	global_store_dword v[20:21], v0, off
	v_mov_b32_e32 v0, v9
	v_mov_b32_e32 v4, v13
	v_mov_b32_e32 v13, v18
	v_pk_mul_f32 v[0:1], v[0:1], v[16:17]
	s_nop 0
	v_pk_fma_f32 v[0:1], v[4:5], v[12:13], v[0:1]
	v_mov_b32_e32 v12, v10
	v_pk_mul_f32 v[0:1], v[132:133], v[0:1] op_sel_hi:[0,1]
	v_cvt_pk_bf16_f32 v0, v0, v1
	global_store_dword v[20:21], v0, off offset:128
	v_add_u32_e32 v0, 0xb2, v130
	v_cndmask_b32_e32 v1, v139, v140, vcc
	v_and_b32_e32 v4, v1, v0
	v_lshl_or_b32 v4, v4, 9, v128
	s_waitcnt vmcnt(31)
	v_mov_b32_e32 v16, v234
	v_mov_b32_e32 v17, v235
	v_mov_b32_e32 v18, v236
	v_mov_b32_e32 v19, v237
	v_mov_b32_e32 v13, v6
	v_mov_b32_e32 v4, v14
	v_mov_b32_e32 v5, v2
	v_mad_i64_i32 v[0:1], s[64:65], v0, s9, v[134:135]
	v_cmp_gt_i32_e32 vcc, s2, v130
	v_mov_b32_e32 v20, v17
	v_mov_b32_e32 v21, v19
	v_mov_b32_e32 v8, v16
	v_mov_b32_e32 v9, v18
	v_pk_mul_f32 v[12:13], v[12:13], v[20:21]
	s_nop 0
	v_pk_fma_f32 v[4:5], v[4:5], v[8:9], v[12:13] neg_lo:[0,0,1] neg_hi:[0,0,1]
	v_mov_b32_e32 v8, v17
	v_pk_mul_f32 v[4:5], v[132:133], v[4:5] op_sel_hi:[0,1]
	v_cvt_pk_bf16_f32 v4, v4, v5
	v_mov_b32_e32 v12, v10
	v_mov_b32_e32 v13, v2
	v_mov_b32_e32 v17, v19
	global_store_dword v[0:1], v4, off
	v_mov_b32_e32 v4, v14
	v_mov_b32_e32 v5, v6
	v_pk_mul_f32 v[12:13], v[12:13], v[16:17]
	v_mov_b32_e32 v6, v11
	v_pk_fma_f32 v[4:5], v[4:5], v[8:9], v[12:13]
	s_nop 0
	v_pk_mul_f32 v[4:5], v[132:133], v[4:5] op_sel_hi:[0,1]
	v_cvt_pk_bf16_f32 v2, v4, v5
	global_store_dword v[0:1], v2, off offset:128
	v_add_u32_e32 v0, 0xb3, v130
	v_cndmask_b32_e32 v1, v139, v140, vcc
	v_and_b32_e32 v2, v1, v0
	v_lshl_or_b32 v2, v2, 9, v128
	s_waitcnt vmcnt(32)
	v_mov_b32_e32 v16, v238
	v_mov_b32_e32 v17, v239
	v_mov_b32_e32 v18, v240
	v_mov_b32_e32 v19, v241
	v_mov_b32_e32 v2, v15
	v_mad_i64_i32 v[0:1], s[64:65], v0, s9, v[134:135]
	v_mov_b32_e32 v8, v17
	v_mov_b32_e32 v9, v19
	v_mov_b32_e32 v4, v16
	v_mov_b32_e32 v5, v18
	v_pk_mul_f32 v[8:9], v[6:7], v[8:9]
	v_mov_b32_e32 v6, v15
	v_pk_fma_f32 v[4:5], v[2:3], v[4:5], v[8:9] neg_lo:[0,0,1] neg_hi:[0,0,1]
	s_nop 0
	v_pk_mul_f32 v[4:5], v[132:133], v[4:5] op_sel_hi:[0,1]
	v_cvt_pk_bf16_f32 v2, v4, v5
	global_store_dword v[0:1], v2, off
	v_mov_b32_e32 v4, v17
	v_mov_b32_e32 v2, v11
	v_mov_b32_e32 v17, v19
	v_mov_b32_e32 v5, v18
	v_pk_mul_f32 v[2:3], v[2:3], v[16:17]
	s_nop 0
	v_pk_fma_f32 v[2:3], v[6:7], v[4:5], v[2:3]
	s_nop 0
	v_pk_mul_f32 v[2:3], v[132:133], v[2:3] op_sel_hi:[0,1]
	v_cvt_pk_bf16_f32 v2, v2, v3
	global_store_dword v[0:1], v2, off offset:128
	s_branch .LBB0_169
